# fused-norm GEMM epilogues (O-proj, down): the residual and gain loads are issued before the LDS-reuse barrier instead of after it; on attention zero-hoist stack
# baseline (speedup 1.0000x reference)
.LBB0_894:
	s_add_u32 s6, s10, 0x15e12000
	s_addc_u32 s7, s11, 0
	s_add_u32 s21, s10, 0x16e12000
	s_mul_i32 s4, s56, 0x9000
	s_mov_b32 s5, s50
	s_addc_u32 s24, s11, 0
	s_lshl_b64 s[4:5], s[4:5], 2
	s_add_u32 s25, s10, s4
	s_addc_u32 s27, s11, s5
	s_lshl_b32 s4, s33, 5
	s_lshl_b32 s26, s20, 8
	s_lshl_b32 s28, s18, 8
	v_lshrrev_b32_e32 v0, 1, v212
	s_add_i32 s5, s26, s80
	s_or_b32 s4, s28, s4
	v_and_or_b32 v208, v0, 24, s4
	s_cmp_lt_i32 s20, 24
	s_movk_i32 s4, 0x3000
	s_cselect_b32 s28, s4, 0x6000
	s_cmp_lt_i32 s20, 16
	s_cselect_b64 vcc, -1, 0
	v_or_b32_e32 v210, s5, v221
	s_and_b64 s[4:5], vcc, exec
	s_cselect_b32 s20, 0, s28
	s_cselect_b32 s4, s6, s21
	s_cselect_b32 s5, s7, s24
	s_lshl_b32 s20, s20, 2
	s_add_u32 s20, s25, s20
	s_addc_u32 s21, s27, 0
	v_lshlrev_b32_e32 v0, 11, v210
	s_add_u32 s20, s20, 0x580000
	v_add_u32_e32 v130, 0x7f800000, v0
	s_addc_u32 s21, s21, 0
	v_ashrrev_i32_e32 v209, 31, v208
	v_cndmask_b32_e32 v0, v130, v0, vcc
	v_lshl_add_u64 v[130:131], v[208:209], 2, s[20:21]
	s_movk_i32 s24, 0x4000
	v_add_lshl_u32 v146, v0, v208, 1
	v_add_co_u32_e32 v132, vcc, s24, v130
	global_load_dwordx4 v[202:205], v146, s[4:5]
	v_addc_co_u32_e32 v133, vcc, 0, v131, vcc
	global_load_dwordx4 v[142:145], v[132:133], off
	s_mov_b64 s[24:25], 0x4000
	v_lshl_add_u64 v[134:135], v[130:131], 0, s[24:25]
	global_load_dwordx4 v[138:141], v[134:135], off offset:16
	global_load_dwordx4 v[214:217], v146, s[4:5] offset:256
	global_load_dwordx4 v[130:133], v[134:135], off offset:528
	s_nop 0
	global_load_dwordx4 v[134:137], v[134:135], off offset:512
	v_add_u32_e32 v147, 0x10000, v146
	v_or_b32_e32 v148, 0x100, v147
	global_load_dwordx4 v[198:201], v147, s[4:5]
	global_load_dwordx4 v[194:197], v148, s[4:5]
	v_add_u32_e32 v147, 0x20000, v146
	v_add_u32_e32 v146, 0x30000, v146
	v_add_u32_e32 v0, 0x40000, v0
	v_or_b32_e32 v148, 0x100, v147
	global_load_dwordx4 v[190:193], v147, s[4:5]
	global_load_dwordx4 v[186:189], v148, s[4:5]
	v_or_b32_e32 v147, 0x100, v146
	global_load_dwordx4 v[178:181], v146, s[4:5]
	global_load_dwordx4 v[174:177], v147, s[4:5]
	v_add_lshl_u32 v146, v0, v208, 1
	v_or_b32_e32 v147, 0x100, v146
	global_load_dwordx4 v[182:185], v146, s[4:5]
	global_load_dwordx4 v[170:173], v147, s[4:5]
	v_or_b32_e32 v146, 0x8000, v0
	v_add_lshl_u32 v146, v146, v208, 1
	v_or_b32_e32 v147, 0x100, v146
	global_load_dwordx4 v[166:169], v146, s[4:5]
	global_load_dwordx4 v[162:165], v147, s[4:5]
	v_or_b32_e32 v146, 0x10000, v0
	v_or_b32_e32 v0, 0x18000, v0
	v_add_lshl_u32 v146, v146, v208, 1
	v_add_lshl_u32 v0, v0, v208, 1
	v_or_b32_e32 v147, 0x100, v146
	global_load_dwordx4 v[158:161], v146, s[4:5]
	global_load_dwordx4 v[154:157], v147, s[4:5]
	v_or_b32_e32 v146, 0x100, v0
	global_load_dwordx4 v[150:153], v0, s[4:5]
	s_nop 0
	global_load_dwordx4 v[146:149], v146, s[4:5]
	v_and_b32_e32 v226, 63, v212
	s_lshl_b32 s4, s33, 2
	s_add_i32 s4, s4, 0
	v_cmp_gt_u32_e32 vcc, 16, v226
	v_lshl_add_u32 v211, v211, 4, s4
	s_barrier
	s_waitcnt vmcnt(0)
	v_lshlrev_b32_e32 v206, 16, v202
	v_and_b32_e32 v207, 0xffff0000, v202
	v_lshlrev_b32_e32 v202, 16, v203
	v_and_b32_e32 v203, 0xffff0000, v203
	v_lshlrev_b32_e32 v218, 16, v204
	v_and_b32_e32 v219, 0xffff0000, v204
	v_lshlrev_b32_e32 v204, 16, v205
	v_and_b32_e32 v205, 0xffff0000, v205
	v_pk_fma_f32 v[128:129], v[128:129], v[144:145], v[202:203]
	v_pk_fma_f32 v[126:127], v[126:127], v[142:143], v[206:207]
	v_pk_fma_f32 v[124:125], v[124:125], v[140:141], v[204:205]
	v_pk_fma_f32 v[122:123], v[122:123], v[138:139], v[218:219]
	v_mul_f32_e32 v0, v127, v127
	v_mul_f32_e32 v202, v129, v129
	v_mul_f32_e32 v203, v123, v123
	v_mul_f32_e32 v204, v125, v125
	v_fmac_f32_e32 v0, v126, v126
	v_fmac_f32_e32 v202, v128, v128
	v_fmac_f32_e32 v203, v122, v122
	v_fmac_f32_e32 v204, v124, v124
	v_add_f32_e32 v0, v0, v202
	v_add_f32_e32 v202, v203, v204
	v_add_f32_e32 v0, v0, v202
	v_lshlrev_b32_e32 v202, 16, v214
	v_and_b32_e32 v203, 0xffff0000, v214
	v_lshlrev_b32_e32 v204, 16, v215
	v_and_b32_e32 v205, 0xffff0000, v215
	v_pk_fma_f32 v[120:121], v[120:121], v[136:137], v[204:205]
	v_pk_fma_f32 v[118:119], v[118:119], v[134:135], v[202:203]
	v_lshlrev_b32_e32 v206, 16, v216
	v_and_b32_e32 v207, 0xffff0000, v216
	v_lshlrev_b32_e32 v214, 16, v217
	v_and_b32_e32 v215, 0xffff0000, v217
	v_mul_f32_e32 v202, v119, v119
	v_mul_f32_e32 v203, v121, v121
	v_pk_fma_f32 v[116:117], v[116:117], v[132:133], v[214:215]
	v_pk_fma_f32 v[114:115], v[114:115], v[130:131], v[206:207]
	v_fmac_f32_e32 v202, v118, v118
	v_fmac_f32_e32 v203, v120, v120
	v_add_f32_e32 v202, v202, v203
	v_mul_f32_e32 v203, v115, v115
	v_mul_f32_e32 v204, v117, v117
	v_fmac_f32_e32 v203, v114, v114
	v_fmac_f32_e32 v204, v116, v116
	v_add_f32_e32 v203, v203, v204
	v_add_f32_e32 v202, v202, v203
	v_lshlrev_b32_e32 v203, 2, v226
	v_add_f32_e32 v202, v0, v202
	v_xor_b32_e32 v0, 64, v203
	v_mov_b32_e32 v204, v202
	s_nop 1
	v_permlane16_swap_b32 v204, v202
	s_nop 1
	v_xor_b32_e32 v213, 0x80, v203
	s_waitcnt lgkmcnt(0)
	v_add_f32_e32 v214, v202, v204
	v_mov_b32_e32 v215, v214
	s_nop 1
	v_permlane32_swap_b32 v215, v214
	s_nop 1
	s_and_saveexec_b64 s[4:5], vcc
	s_cbranch_execz .LBB0_896
	s_waitcnt lgkmcnt(0)
	v_add_f32_e32 v202, v214, v215
	ds_write_b32 v211, v202

.LBB0_954:
	s_lshl_b32 s4, s33, 5
	s_lshl_b32 s26, s18, 8
	s_lshl_b32 s6, s16, 8
	v_lshrrev_b32_e32 v0, 1, v220
	s_add_i32 s5, s26, s86
	s_or_b32 s4, s6, s4
	v_and_or_b32 v146, v0, 24, s4
	s_cmp_lt_i32 s18, 24
	s_movk_i32 s4, 0x3000
	s_cselect_b32 s19, s4, 0x6000
	s_cmp_lt_i32 s18, 16
	v_or_b32_e32 v150, s5, v221
	s_cselect_b64 s[4:5], -1, 0
	s_and_b64 s[6:7], s[4:5], exec
	s_cselect_b32 s6, 0, s19
	s_cselect_b32 s19, s21, s25
	s_cselect_b32 s18, s20, s24
	s_lshl_b32 s6, s6, 2
	s_add_u32 s6, s10, s6
	s_addc_u32 s7, s11, 0
	v_add_u32_e32 v0, 0xfffff000, v150
	s_add_u32 s6, s6, 0x580000
	v_ashrrev_i32_e32 v147, 31, v146
	v_cndmask_b32_e64 v114, v0, v150, s[4:5]
	s_addc_u32 s7, s7, 0
	v_lshlrev_b64 v[148:149], 2, v[146:147]
	v_lshl_add_u64 v[116:117], s[6:7], 0, v[148:149]
	s_movk_i32 s20, 0x4000
	v_ashrrev_i32_e32 v115, 31, v114
	v_add_co_u32_e32 v118, vcc, s20, v116
	v_lshlrev_b64 v[114:115], 13, v[114:115]
	s_nop 0
	v_addc_co_u32_e32 v119, vcc, 0, v117, vcc
	v_lshl_add_u64 v[114:115], s[18:19], 0, v[114:115]
	global_load_dwordx4 v[122:125], v[118:119], off
	v_lshl_add_u64 v[118:119], v[114:115], 0, v[148:149]
	global_load_dwordx4 v[152:155], v[118:119], off offset:16
	global_load_dwordx4 v[156:159], v[118:119], off
	s_mov_b64 s[20:21], 0x4000
	v_lshl_add_u64 v[120:121], v[116:117], 0, s[20:21]
	global_load_dwordx4 v[126:129], v[120:121], off offset:16
	global_load_dwordx4 v[114:117], v[120:121], off offset:512
	global_load_dwordx4 v[160:163], v[118:119], off offset:512
	global_load_dwordx4 v[164:167], v[118:119], off offset:528
	s_nop 0
	global_load_dwordx4 v[118:121], v[120:121], off offset:528
	v_and_b32_e32 v226, 63, v220
	v_lshlrev_b32_e32 v168, 2, v226
	v_xor_b32_e32 v0, 64, v168
	s_lshl_b32 s20, s33, 2
	s_add_i32 s20, s20, 0
	v_cmp_gt_u32_e32 vcc, 16, v226
	v_lshl_add_u32 v151, v151, 4, s20
	s_barrier
	s_waitcnt vmcnt(0)
	v_pk_fma_f32 v[140:141], v[140:141], v[128:129], v[154:155]
	v_pk_fma_f32 v[144:145], v[144:145], v[124:125], v[158:159]
	v_pk_fma_f32 v[142:143], v[142:143], v[122:123], v[156:157]
	v_pk_fma_f32 v[138:139], v[138:139], v[126:127], v[152:153]
	v_pk_fma_f32 v[136:137], v[136:137], v[116:117], v[162:163]
	v_pk_fma_f32 v[134:135], v[134:135], v[114:115], v[160:161]
	v_mul_f32_e32 v152, v143, v143
	v_mul_f32_e32 v153, v145, v145
	v_mul_f32_e32 v154, v139, v139
	v_mul_f32_e32 v155, v141, v141
	v_pk_fma_f32 v[132:133], v[132:133], v[120:121], v[166:167]
	v_pk_fma_f32 v[130:131], v[130:131], v[118:119], v[164:165]
	v_mul_f32_e32 v156, v135, v135
	v_mul_f32_e32 v157, v137, v137
	v_fmac_f32_e32 v152, v142, v142
	v_fmac_f32_e32 v153, v144, v144
	v_fmac_f32_e32 v154, v138, v138
	v_fmac_f32_e32 v155, v140, v140
	v_mul_f32_e32 v158, v131, v131
	v_mul_f32_e32 v159, v133, v133
	v_fmac_f32_e32 v156, v134, v134
	v_fmac_f32_e32 v157, v136, v136
	v_add_f32_e32 v152, v152, v153
	v_add_f32_e32 v153, v154, v155
	v_fmac_f32_e32 v158, v130, v130
	v_fmac_f32_e32 v159, v132, v132
	v_add_f32_e32 v154, v156, v157
	v_add_f32_e32 v152, v152, v153
	v_add_f32_e32 v152, v152, v154
	v_add_f32_e32 v153, v158, v159
	v_add_f32_e32 v152, v152, v153
	v_mov_b32_e32 v153, v152
	s_nop 1
	v_permlane16_swap_b32 v153, v152
	s_nop 1
	v_xor_b32_e32 v161, 0x80, v168
	s_waitcnt lgkmcnt(0)
	v_add_f32_e32 v152, v152, v153
	v_mov_b32_e32 v153, v152
	s_nop 1
	v_permlane32_swap_b32 v153, v152
	s_nop 1
	s_and_saveexec_b64 s[20:21], vcc
	s_cbranch_execz .LBB0_956
	s_waitcnt lgkmcnt(0)
	v_add_f32_e32 v152, v152, v153
	ds_write_b32 v151, v152

.LBB0_1207:
	s_mul_i32 s5, s56, 0x24000
	s_mul_hi_u32 s4, s56, 0x24000
	s_add_u32 s5, s26, s5
	s_addc_u32 s4, s27, s4
	s_add_u32 s22, s5, 0x580000
	s_addc_u32 s23, s4, 0
	s_lshl_b32 s4, s33, 5
	s_add_u32 s8, s26, 0x15e12000
	s_addc_u32 s9, s27, 0
	s_add_u32 s6, s26, 0x16e12000
	s_addc_u32 s7, s27, 0
	s_lshl_b32 s20, s39, 8
	s_lshl_b32 s18, s16, 8
	v_lshrrev_b32_e32 v0, 1, v213
	s_add_i32 s5, s20, s34
	s_or_b32 s4, s18, s4
	v_and_or_b32 v208, v0, 24, s4
	s_cmp_lt_i32 s39, 24
	s_movk_i32 s4, 0x3000
	s_cselect_b32 s18, s4, 0x6000
	s_cmp_lt_i32 s39, 16
	s_cselect_b64 vcc, -1, 0
	v_or_b32_e32 v210, s5, v212
	s_and_b64 s[4:5], vcc, exec
	s_cselect_b32 s18, 0, s18
	v_lshlrev_b32_e32 v0, 11, v210
	s_cselect_b32 s5, s9, s7
	s_cselect_b32 s4, s8, s6
	s_lshl_b32 s21, s18, 2
	v_add_u32_e32 v130, 0x7f800000, v0
	s_add_u32 s6, s22, s21
	v_cndmask_b32_e32 v0, v130, v0, vcc
	s_addc_u32 s7, s23, 0
	v_ashrrev_i32_e32 v209, 31, v208
	v_add_lshl_u32 v146, v0, v208, 1
	v_lshl_add_u64 v[130:131], v[208:209], 2, s[6:7]
	s_mov_b32 s6, 0xa000
	global_load_dwordx4 v[202:205], v146, s[4:5]
	v_add_co_u32_e32 v132, vcc, s6, v130
	s_mov_b64 s[6:7], 0xa000
	s_nop 0
	v_addc_co_u32_e32 v133, vcc, 0, v131, vcc
	global_load_dwordx4 v[216:219], v146, s[4:5] offset:256
	global_load_dwordx4 v[142:145], v[132:133], off
	v_lshl_add_u64 v[134:135], v[130:131], 0, s[6:7]
	global_load_dwordx4 v[138:141], v[134:135], off offset:16
	global_load_dwordx4 v[130:133], v[134:135], off offset:528
	s_nop 0
	global_load_dwordx4 v[134:137], v[134:135], off offset:512
	v_add_u32_e32 v147, 0x10000, v146
	v_or_b32_e32 v148, 0x100, v147
	global_load_dwordx4 v[198:201], v147, s[4:5]
	global_load_dwordx4 v[194:197], v148, s[4:5]
	v_add_u32_e32 v147, 0x20000, v146
	v_add_u32_e32 v146, 0x30000, v146
	v_add_u32_e32 v0, 0x40000, v0
	v_or_b32_e32 v148, 0x100, v147
	global_load_dwordx4 v[190:193], v147, s[4:5]
	global_load_dwordx4 v[186:189], v148, s[4:5]
	v_or_b32_e32 v147, 0x100, v146
	global_load_dwordx4 v[178:181], v146, s[4:5]
	global_load_dwordx4 v[174:177], v147, s[4:5]
	v_add_lshl_u32 v146, v0, v208, 1
	v_or_b32_e32 v147, 0x100, v146
	global_load_dwordx4 v[182:185], v146, s[4:5]
	global_load_dwordx4 v[170:173], v147, s[4:5]
	v_or_b32_e32 v146, 0x8000, v0
	v_add_lshl_u32 v146, v146, v208, 1
	v_or_b32_e32 v147, 0x100, v146
	global_load_dwordx4 v[166:169], v146, s[4:5]
	global_load_dwordx4 v[162:165], v147, s[4:5]
	v_or_b32_e32 v146, 0x10000, v0
	v_or_b32_e32 v0, 0x18000, v0
	v_add_lshl_u32 v146, v146, v208, 1
	v_add_lshl_u32 v0, v0, v208, 1
	v_or_b32_e32 v147, 0x100, v146
	global_load_dwordx4 v[158:161], v146, s[4:5]
	global_load_dwordx4 v[154:157], v147, s[4:5]
	v_or_b32_e32 v146, 0x100, v0
	global_load_dwordx4 v[150:153], v0, s[4:5]
	s_nop 0
	global_load_dwordx4 v[146:149], v146, s[4:5]
	v_and_b32_e32 v214, 63, v213
	s_lshl_b32 s4, s33, 2
	s_add_i32 s4, s4, 0
	v_cmp_gt_u32_e32 vcc, 16, v214
	v_lshl_add_u32 v211, v211, 4, s4
	s_barrier
	s_waitcnt vmcnt(0)
	v_lshlrev_b32_e32 v206, 16, v202
	v_and_b32_e32 v207, 0xffff0000, v202
	v_lshlrev_b32_e32 v202, 16, v203
	v_and_b32_e32 v203, 0xffff0000, v203
	v_lshlrev_b32_e32 v220, 16, v204
	v_and_b32_e32 v221, 0xffff0000, v204
	v_lshlrev_b32_e32 v204, 16, v205
	v_and_b32_e32 v205, 0xffff0000, v205
	v_pk_fma_f32 v[128:129], v[128:129], v[144:145], v[202:203]
	v_pk_fma_f32 v[126:127], v[126:127], v[142:143], v[206:207]
	v_pk_fma_f32 v[124:125], v[124:125], v[140:141], v[204:205]
	v_pk_fma_f32 v[122:123], v[122:123], v[138:139], v[220:221]
	v_mul_f32_e32 v0, v127, v127
	v_mul_f32_e32 v202, v129, v129
	v_mul_f32_e32 v203, v123, v123
	v_mul_f32_e32 v204, v125, v125
	v_fmac_f32_e32 v0, v126, v126
	v_fmac_f32_e32 v202, v128, v128
	v_fmac_f32_e32 v203, v122, v122
	v_fmac_f32_e32 v204, v124, v124
	v_add_f32_e32 v0, v0, v202
	v_add_f32_e32 v202, v203, v204
	v_lshlrev_b32_e32 v222, 16, v216
	v_add_f32_e32 v0, v0, v202
	v_and_b32_e32 v223, 0xffff0000, v216
	v_lshlrev_b32_e32 v202, 16, v217
	v_and_b32_e32 v203, 0xffff0000, v217
	v_pk_fma_f32 v[120:121], v[120:121], v[136:137], v[202:203]
	v_pk_fma_f32 v[118:119], v[118:119], v[134:135], v[222:223]
	v_lshlrev_b32_e32 v204, 16, v218
	v_and_b32_e32 v205, 0xffff0000, v218
	v_lshlrev_b32_e32 v206, 16, v219
	v_and_b32_e32 v207, 0xffff0000, v219
	v_mul_f32_e32 v202, v119, v119
	v_mul_f32_e32 v203, v121, v121
	v_pk_fma_f32 v[116:117], v[116:117], v[132:133], v[206:207]
	v_pk_fma_f32 v[114:115], v[114:115], v[130:131], v[204:205]
	v_fmac_f32_e32 v202, v118, v118
	v_fmac_f32_e32 v203, v120, v120
	v_add_f32_e32 v202, v202, v203
	v_mul_f32_e32 v203, v115, v115
	v_mul_f32_e32 v204, v117, v117
	v_fmac_f32_e32 v203, v114, v114
	v_fmac_f32_e32 v204, v116, v116
	v_add_f32_e32 v203, v203, v204
	v_add_f32_e32 v202, v202, v203
	v_lshlrev_b32_e32 v203, 2, v214
	v_add_f32_e32 v202, v0, v202
	v_xor_b32_e32 v0, 64, v203
	v_mov_b32_e32 v204, v202
	s_nop 1
	v_permlane16_swap_b32 v204, v202
	s_nop 1
	v_xor_b32_e32 v215, 0x80, v203
	s_waitcnt lgkmcnt(0)
	v_add_f32_e32 v216, v202, v204
	v_mov_b32_e32 v217, v216
	s_nop 1
	v_permlane32_swap_b32 v217, v216
	s_nop 1
	s_and_saveexec_b64 s[4:5], vcc
	s_cbranch_execz .LBB0_1209
	s_waitcnt lgkmcnt(0)
	v_add_f32_e32 v202, v216, v217
	ds_write_b32 v211, v202
